# attention loops: removed 16 v_mov_b64 register copies per 2 key tiles (MFMA C operand reads the -mref broadcast directly; second score block accumulates in place) and folded 0+x partial-sum adds
# speedup vs baseline: 1.0230x; 1.0040x over previous
.LBB0_729:
.LBB0_730:
	s_add_i32 s25, s60, 1
	s_and_b32 s24, s25, 3
	s_mul_i32 s23, s24, 0x3400
	v_add_u32_e32 v80, s23, v227
	ds_read_b128 v[164:167], v80
	ds_read_b128 v[168:171], v80 offset:32
	ds_read_b128 v[172:175], v80 offset:6656
	ds_read_b128 v[176:179], v80 offset:6688
	ds_read_b128 v[180:183], v80 offset:64
	ds_read_b128 v[184:187], v80 offset:96
	ds_read_b128 v[188:191], v80 offset:6720
	ds_read_b128 v[192:195], v80 offset:6752
	ds_read_b128 v[236:239], v80 offset:128
	ds_read_b128 v[240:243], v80 offset:160
	ds_read_b128 v[244:247], v80 offset:6784
	ds_read_b128 v[160:163], v80 offset:6816
	s_waitcnt lgkmcnt(11)
	v_mfma_f32_32x32x16_bf16 v[80:95], v[164:167], v[112:115], v[32:47]
	v_exp_f32_e32 v64, v64
	v_exp_f32_e32 v66, v66
	v_exp_f32_e32 v68, v68
	v_exp_f32_e32 v164, v96
	v_exp_f32_e32 v65, v65
	v_exp_f32_e32 v165, v97
	v_exp_f32_e32 v70, v70
	v_add_f32_e32 v96, v66, v64
	v_exp_f32_e32 v67, v67
	v_add_f32_e32 v96, v68, v96
	v_add_f32_e32 v96, v70, v96
	s_waitcnt lgkmcnt(10)
	v_mfma_f32_32x32x16_bf16 v[80:95], v[168:171], v[116:119], v[80:95]
	v_exp_f32_e32 v169, v99
	v_exp_f32_e32 v168, v98
	v_add_f32_e32 v98, v67, v65
	v_exp_f32_e32 v166, v100
	v_add_f32_e32 v99, v169, v165
	v_exp_f32_e32 v69, v69
	v_exp_f32_e32 v167, v101
	v_exp_f32_e32 v170, v102
	v_add_f32_e32 v97, v168, v164
	v_add_f32_e32 v97, v166, v97
	v_add_f32_e32 v98, v69, v98
	v_add_f32_e32 v99, v167, v99
	v_add_f32_e32 v97, v170, v97
	s_waitcnt lgkmcnt(7)
	v_mfma_f32_32x32x16_bf16 v[80:95], v[180:183], v[120:123], v[80:95]
	v_exp_f32_e32 v71, v71
	v_exp_f32_e32 v171, v103
	v_exp_f32_e32 v180, v72
	v_exp_f32_e32 v181, v104
	v_exp_f32_e32 v182, v73
	v_exp_f32_e32 v183, v105
	v_add_f32_e32 v98, v71, v98
	v_add_f32_e32 v99, v171, v99
	v_add_f32_e32 v72, v180, v96
	v_add_f32_e32 v73, v181, v97
	v_add_f32_e32 v96, v182, v98
	v_add_f32_e32 v97, v183, v99
	v_exp_f32_e32 v235, v76
	v_cvt_pk_bf16_f32 v76, v180, v182
	s_waitcnt lgkmcnt(6)
	v_mfma_f32_32x32x16_bf16 v[80:95], v[184:187], v[124:127], v[80:95]
	v_exp_f32_e32 v184, v74
	v_exp_f32_e32 v185, v106
	v_exp_f32_e32 v186, v75
	v_exp_f32_e32 v187, v107
	v_add_f32_e32 v72, v184, v72
	v_add_f32_e32 v73, v185, v73
	v_add_f32_e32 v74, v186, v96
	v_add_f32_e32 v75, v187, v97
	v_add_f32_e32 v72, v235, v72
	s_waitcnt lgkmcnt(3)
	v_mfma_f32_32x32x16_bf16 v[80:95], v[236:239], v[128:131], v[80:95]
	v_exp_f32_e32 v237, v77
	v_exp_f32_e32 v236, v108
	v_exp_f32_e32 v238, v109
	v_exp_f32_e32 v239, v78
	v_exp_f32_e32 v79, v79
	v_add_f32_e32 v74, v237, v74
	v_add_f32_e32 v73, v236, v73
	v_add_f32_e32 v75, v238, v75
	v_add_f32_e32 v72, v239, v72
	v_add_f32_e32 v74, v79, v74
	v_cvt_pk_bf16_f32 v77, v184, v186
	v_cvt_pk_bf16_f32 v78, v235, v237
	s_waitcnt lgkmcnt(2)
	v_mfma_f32_32x32x16_bf16 v[80:95], v[240:243], v[132:135], v[80:95]
	v_exp_f32_e32 v240, v110
	v_exp_f32_e32 v241, v111
	v_cvt_pk_bf16_f32 v79, v239, v79
	v_add_f32_e32 v73, v240, v73
	v_add_f32_e32 v75, v241, v75
	v_add_f32_e32 v72, v73, v72
	v_add_f32_e32 v73, v75, v74
	v_cvt_pk_bf16_f32 v74, v68, v69
	v_cvt_pk_bf16_f32 v75, v70, v71
	v_mfma_f32_32x32x16_bf16 v[96:111], v[172:175], v[112:115], v[32:47]
	v_add_f32_e32 v172, v73, v72
	v_cvt_pk_bf16_f32 v72, v64, v65
	v_cvt_pk_bf16_f32 v73, v66, v67
	v_cvt_pk_bf16_f32 v64, v164, v165
	v_cvt_pk_bf16_f32 v65, v168, v169
	v_cvt_pk_bf16_f32 v66, v166, v167
	v_cvt_pk_bf16_f32 v67, v170, v171
	v_mfma_f32_32x32x16_bf16 v[96:111], v[176:179], v[116:119], v[96:111]
	v_cvt_pk_bf16_f32 v68, v181, v183
	v_cvt_pk_bf16_f32 v69, v185, v187
	v_cvt_pk_bf16_f32 v70, v236, v238
	v_cvt_pk_bf16_f32 v71, v240, v241
	v_add_f32_e32 v234, v234, v172
	v_mfma_f32_32x32x16_bf16 v[96:111], v[188:191], v[120:123], v[96:111]
	v_mfma_f32_32x32x16_bf16 v[96:111], v[192:195], v[124:127], v[96:111]
	s_waitcnt lgkmcnt(1)
	v_mfma_f32_32x32x16_bf16 v[96:111], v[244:247], v[128:131], v[96:111]
	s_and_b32 s23, s60, 2
	s_waitcnt lgkmcnt(0)
	v_mfma_f32_32x32x16_bf16 v[96:111], v[160:163], v[132:135], v[96:111]
	s_mul_i32 s26, s23, 0x3000
	v_add_u32_e32 v164, s26, v232
	ds_read_b64_tr_b16 v[192:193], v164 offset:53248
	ds_read_b64_tr_b16 v[194:195], v164 offset:54784
	ds_read_b64_tr_b16 v[190:191], v164 offset:54848
	ds_read_b64_tr_b16 v[188:189], v164 offset:53312
	ds_read_b64_tr_b16 v[184:185], v164 offset:56320
	ds_read_b64_tr_b16 v[186:187], v164 offset:57856
	ds_read_b64_tr_b16 v[182:183], v164 offset:57920
	ds_read_b64_tr_b16 v[180:181], v164 offset:56384
	ds_read_b64_tr_b16 v[176:177], v164 offset:59392
	ds_read_b64_tr_b16 v[178:179], v164 offset:60928
	ds_read_b64_tr_b16 v[174:175], v164 offset:60992
	ds_read_b64_tr_b16 v[172:173], v164 offset:59456
	ds_read_b64_tr_b16 v[168:169], v164 offset:62464
	ds_read_b64_tr_b16 v[170:171], v164 offset:64000
	ds_read_b64_tr_b16 v[166:167], v164 offset:64064
	ds_read_b64_tr_b16 v[164:165], v164 offset:62528
	s_cmp_lt_u32 s25, s7
	s_cbranch_scc1 .LBB0_732
	v_add_u32_e32 v160, 32, v233
	v_cmp_le_i32_e32 vcc, v160, v229
	v_add_u32_e32 v160, 33, v233
	s_nop 0
	v_cndmask_b32_e32 v96, v224, v96, vcc
	v_cmp_lt_i32_e32 vcc, v233, v229
	s_nop 1
	v_cndmask_b32_e32 v81, v224, v81, vcc
	v_cmp_le_i32_e32 vcc, v233, v229
	s_nop 1
	v_cndmask_b32_e32 v80, v224, v80, vcc
	v_cmp_le_i32_e32 vcc, v160, v229
	v_add_u32_e32 v160, 2, v233
	s_nop 0
	v_cndmask_b32_e32 v97, v224, v97, vcc
	v_cmp_le_i32_e32 vcc, v160, v229
	v_add_u32_e32 v160, 34, v233
	s_nop 0
	v_cndmask_b32_e32 v82, v224, v82, vcc
	v_cmp_le_i32_e32 vcc, v160, v229
	v_add_u32_e32 v160, 3, v233
	s_nop 0
	v_cndmask_b32_e32 v98, v224, v98, vcc
	v_cmp_le_i32_e32 vcc, v160, v229
	v_add_u32_e32 v160, 35, v233
	s_nop 0
	v_cndmask_b32_e32 v83, v224, v83, vcc
	v_cmp_le_i32_e32 vcc, v160, v229
	v_add_u32_e32 v160, 8, v233
	s_nop 0
	v_cndmask_b32_e32 v99, v224, v99, vcc
	v_cmp_le_i32_e32 vcc, v160, v229
	v_add_u32_e32 v160, 40, v233
	s_nop 0
	v_cndmask_b32_e32 v84, v224, v84, vcc
	v_cmp_le_i32_e32 vcc, v160, v229
	v_add_u32_e32 v160, 9, v233
	s_nop 0
	v_cndmask_b32_e32 v100, v224, v100, vcc
	v_cmp_le_i32_e32 vcc, v160, v229
	v_add_u32_e32 v160, 41, v233
	s_nop 0
	v_cndmask_b32_e32 v85, v224, v85, vcc
	v_cmp_le_i32_e32 vcc, v160, v229
	v_add_u32_e32 v160, 10, v233
	s_nop 0
	v_cndmask_b32_e32 v101, v224, v101, vcc
	v_cmp_le_i32_e32 vcc, v160, v229
	v_add_u32_e32 v160, 42, v233
	s_nop 0
	v_cndmask_b32_e32 v86, v224, v86, vcc
	v_cmp_le_i32_e32 vcc, v160, v229
	v_add_u32_e32 v160, 11, v233
	s_nop 0
	v_cndmask_b32_e32 v102, v224, v102, vcc
	v_cmp_le_i32_e32 vcc, v160, v229
	v_add_u32_e32 v160, 43, v233
	s_nop 0
	v_cndmask_b32_e32 v87, v224, v87, vcc
	v_cmp_le_i32_e32 vcc, v160, v229
	v_add_u32_e32 v160, 16, v233
	s_nop 0
	v_cndmask_b32_e32 v103, v224, v103, vcc
	v_cmp_le_i32_e32 vcc, v160, v229
	v_add_u32_e32 v160, 48, v233
	s_nop 0
	v_cndmask_b32_e32 v88, v224, v88, vcc
	v_cmp_le_i32_e32 vcc, v160, v229
	v_add_u32_e32 v160, 17, v233
	s_nop 0
	v_cndmask_b32_e32 v104, v224, v104, vcc
	v_cmp_le_i32_e32 vcc, v160, v229
	v_add_u32_e32 v160, 49, v233
	s_nop 0
	v_cndmask_b32_e32 v89, v224, v89, vcc
	v_cmp_le_i32_e32 vcc, v160, v229
	v_add_u32_e32 v160, 18, v233
	s_nop 0
	v_cndmask_b32_e32 v105, v224, v105, vcc
	v_cmp_le_i32_e32 vcc, v160, v229
	v_add_u32_e32 v160, 50, v233
	s_nop 0
	v_cndmask_b32_e32 v90, v224, v90, vcc
	v_cmp_le_i32_e32 vcc, v160, v229
	v_add_u32_e32 v160, 19, v233
	s_nop 0
	v_cndmask_b32_e32 v106, v224, v106, vcc
	v_cmp_le_i32_e32 vcc, v160, v229
	v_add_u32_e32 v160, 51, v233
	s_nop 0
	v_cndmask_b32_e32 v91, v224, v91, vcc
	v_cmp_le_i32_e32 vcc, v160, v229
	v_add_u32_e32 v160, 24, v233
	s_nop 0
	v_cndmask_b32_e32 v107, v224, v107, vcc
	v_cmp_le_i32_e32 vcc, v160, v229
	v_add_u32_e32 v160, 56, v233
	s_nop 0
	v_cndmask_b32_e32 v92, v224, v92, vcc
	v_cmp_le_i32_e32 vcc, v160, v229
	v_add_u32_e32 v160, 25, v233
	s_nop 0
	v_cndmask_b32_e32 v108, v224, v108, vcc
	v_cmp_le_i32_e32 vcc, v160, v229
	v_add_u32_e32 v160, 57, v233
	s_nop 0
	v_cndmask_b32_e32 v93, v224, v93, vcc
	v_cmp_le_i32_e32 vcc, v160, v229
	v_add_u32_e32 v160, 26, v233
	s_nop 0
	v_cndmask_b32_e32 v109, v224, v109, vcc
	v_cmp_le_i32_e32 vcc, v160, v229
	v_add_u32_e32 v160, 58, v233
	s_nop 0
	v_cndmask_b32_e32 v94, v224, v94, vcc
	v_cmp_le_i32_e32 vcc, v160, v229
	v_add_u32_e32 v160, 27, v233
	s_nop 0
	v_cndmask_b32_e32 v110, v224, v110, vcc
	v_cmp_le_i32_e32 vcc, v160, v229
	v_add_u32_e32 v160, 59, v233
	s_nop 0
	v_cndmask_b32_e32 v95, v224, v95, vcc
	v_cmp_le_i32_e32 vcc, v160, v229
	s_nop 1
	v_cndmask_b32_e32 v111, v224, v111, vcc

.LBB0_734:
	s_and_b32 s25, s17, 2
	s_mul_i32 s26, s25, 0x3400
	v_add_u32_e32 v64, s26, v227
	ds_read_b128 v[164:167], v64
	ds_read_b128 v[168:171], v64 offset:32
	ds_read_b128 v[172:175], v64 offset:6656
	ds_read_b128 v[176:179], v64 offset:6688
	ds_read_b128 v[180:183], v64 offset:64
	ds_read_b128 v[184:187], v64 offset:96
	ds_read_b128 v[188:191], v64 offset:6720
	ds_read_b128 v[192:195], v64 offset:6752
	ds_read_b128 v[236:239], v64 offset:128
	ds_read_b128 v[240:243], v64 offset:160
	ds_read_b128 v[244:247], v64 offset:6784
	ds_read_b128 v[160:163], v64 offset:6816
	s_waitcnt lgkmcnt(11)
	v_mfma_f32_32x32x16_bf16 v[64:79], v[164:167], v[112:115], v[32:47]
	v_exp_f32_e32 v80, v80
	v_exp_f32_e32 v96, v96
	v_exp_f32_e32 v81, v81
	v_exp_f32_e32 v97, v97
	v_exp_f32_e32 v82, v82
	v_exp_f32_e32 v98, v98
	v_exp_f32_e32 v83, v83
	v_add_f32_e32 v164, v82, v80
	v_add_f32_e32 v165, v98, v96
	v_add_f32_e32 v166, v83, v81
	s_waitcnt lgkmcnt(10)
	v_mfma_f32_32x32x16_bf16 v[64:79], v[168:171], v[116:119], v[64:79]
	v_exp_f32_e32 v99, v99
	v_exp_f32_e32 v84, v84
	v_exp_f32_e32 v100, v100
	v_exp_f32_e32 v85, v85
	v_exp_f32_e32 v101, v101
	v_exp_f32_e32 v86, v86
	v_exp_f32_e32 v102, v102
	v_add_f32_e32 v167, v99, v97
	v_add_f32_e32 v164, v84, v164
	v_add_f32_e32 v165, v100, v165
	v_exp_f32_e32 v87, v87
	v_add_f32_e32 v166, v85, v166
	v_add_f32_e32 v167, v101, v167
	v_add_f32_e32 v164, v86, v164
	v_add_f32_e32 v165, v102, v165
	s_waitcnt lgkmcnt(7)
	v_mfma_f32_32x32x16_bf16 v[64:79], v[180:183], v[120:123], v[64:79]
	v_exp_f32_e32 v168, v88
	v_exp_f32_e32 v169, v89
	v_exp_f32_e32 v103, v103
	v_add_f32_e32 v166, v87, v166
	v_exp_f32_e32 v104, v104
	v_exp_f32_e32 v105, v105
	v_add_f32_e32 v88, v168, v164
	v_add_f32_e32 v164, v169, v166
	v_exp_f32_e32 v166, v90
	v_add_f32_e32 v167, v103, v167
	v_add_f32_e32 v89, v104, v165
	v_add_f32_e32 v165, v105, v167
	v_exp_f32_e32 v167, v91
	v_exp_f32_e32 v107, v107
	v_add_f32_e32 v88, v166, v88
	s_waitcnt lgkmcnt(6)
	v_mfma_f32_32x32x16_bf16 v[64:79], v[184:187], v[124:127], v[64:79]
	v_exp_f32_e32 v106, v106
	v_add_f32_e32 v90, v167, v164
	v_add_f32_e32 v91, v107, v165
	v_exp_f32_e32 v164, v92
	v_exp_f32_e32 v108, v108
	v_exp_f32_e32 v165, v93
	v_exp_f32_e32 v109, v109
	v_add_f32_e32 v89, v106, v89
	v_add_f32_e32 v88, v164, v88
	v_add_f32_e32 v89, v108, v89
	v_add_f32_e32 v90, v165, v90
	v_add_f32_e32 v91, v109, v91
	s_waitcnt lgkmcnt(3)
	v_mfma_f32_32x32x16_bf16 v[64:79], v[236:239], v[128:131], v[64:79]
	v_exp_f32_e32 v170, v94
	v_exp_f32_e32 v110, v110
	v_exp_f32_e32 v95, v95
	v_exp_f32_e32 v111, v111
	v_add_f32_e32 v88, v170, v88
	v_add_f32_e32 v89, v110, v89
	v_add_f32_e32 v90, v95, v90
	v_add_f32_e32 v91, v111, v91
	v_add_f32_e32 v88, v89, v88
	v_add_f32_e32 v89, v91, v90
	v_add_f32_e32 v171, v88, v89
	s_waitcnt lgkmcnt(2)
	v_mfma_f32_32x32x16_bf16 v[64:79], v[240:243], v[132:135], v[64:79]
	v_cvt_pk_bf16_f32 v88, v80, v81
	v_cvt_pk_bf16_f32 v89, v82, v83
	v_cvt_pk_bf16_f32 v90, v84, v85
	v_cvt_pk_bf16_f32 v91, v86, v87
	v_cvt_pk_bf16_f32 v80, v96, v97
	v_cvt_pk_bf16_f32 v81, v98, v99
	v_cvt_pk_bf16_f32 v82, v100, v101
	v_cvt_pk_bf16_f32 v83, v102, v103
	v_cvt_pk_bf16_f32 v84, v104, v105
	v_cvt_pk_bf16_f32 v85, v106, v107
	v_cvt_pk_bf16_f32 v86, v108, v109
	v_cvt_pk_bf16_f32 v87, v110, v111
	v_mfma_f32_32x32x16_bf16 v[96:111], v[172:175], v[112:115], v[32:47]
	v_cvt_pk_bf16_f32 v92, v168, v169
	v_cvt_pk_bf16_f32 v93, v166, v167
	v_cvt_pk_bf16_f32 v94, v164, v165
	v_cvt_pk_bf16_f32 v95, v170, v95
	v_mfma_f32_32x32x16_bf16 v[96:111], v[176:179], v[116:119], v[96:111]
	v_add_f32_e32 v234, v234, v171
	v_mfma_f32_32x32x16_bf16 v[96:111], v[188:191], v[120:123], v[96:111]
	v_mfma_f32_32x32x16_bf16 v[96:111], v[192:195], v[124:127], v[96:111]
	s_waitcnt lgkmcnt(1)
	v_mfma_f32_32x32x16_bf16 v[96:111], v[244:247], v[128:131], v[96:111]
	s_mulk_i32 s24, 0x3000
	v_add_u32_e32 v253, s24, v232
	ds_read_b64_tr_b16 v[192:193], v253 offset:53248
	ds_read_b64_tr_b16 v[194:195], v253 offset:54784
	ds_read_b64_tr_b16 v[190:191], v253 offset:54848
	ds_read_b64_tr_b16 v[188:189], v253 offset:53312
	ds_read_b64_tr_b16 v[184:185], v253 offset:56320
	ds_read_b64_tr_b16 v[186:187], v253 offset:57856
	ds_read_b64_tr_b16 v[182:183], v253 offset:57920
	ds_read_b64_tr_b16 v[180:181], v253 offset:56384
	ds_read_b64_tr_b16 v[176:177], v253 offset:59392
	ds_read_b64_tr_b16 v[178:179], v253 offset:60928
	ds_read_b64_tr_b16 v[174:175], v253 offset:60992
	ds_read_b64_tr_b16 v[172:173], v253 offset:59456
	ds_read_b64_tr_b16 v[168:169], v253 offset:62464
	ds_read_b64_tr_b16 v[170:171], v253 offset:64000
	ds_read_b64_tr_b16 v[166:167], v253 offset:64064
	ds_read_b64_tr_b16 v[164:165], v253 offset:62528
	s_cmp_lt_u32 s17, s7
	s_waitcnt lgkmcnt(14)
	v_mfma_f32_32x32x16_bf16 v[96:111], v[160:163], v[132:135], v[96:111]
	s_cbranch_scc1 .LBB0_736
	v_add_u32_e32 v49, 0x60, v233
	v_add_u32_e32 v48, 64, v233
	v_cmp_le_i32_e32 vcc, v49, v229
	s_nop 7
	v_cndmask_b32_e32 v96, v224, v96, vcc
	v_cmp_lt_i32_e32 vcc, v48, v229
	s_nop 1
	v_cndmask_b32_e32 v65, v224, v65, vcc
	v_cmp_le_i32_e32 vcc, v48, v229
	v_add_u32_e32 v48, 0x61, v233
	s_nop 0
	v_cndmask_b32_e32 v64, v224, v64, vcc
	v_cmp_le_i32_e32 vcc, v48, v229
	v_add_u32_e32 v48, 0x42, v233
	s_nop 0
	v_cndmask_b32_e32 v97, v224, v97, vcc
	v_cmp_le_i32_e32 vcc, v48, v229
	v_add_u32_e32 v48, 0x62, v233
	s_nop 0
	v_cndmask_b32_e32 v66, v224, v66, vcc
	v_cmp_le_i32_e32 vcc, v48, v229
	v_add_u32_e32 v48, 0x43, v233
	s_nop 0
	v_cndmask_b32_e32 v98, v224, v98, vcc
	v_cmp_le_i32_e32 vcc, v48, v229
	v_add_u32_e32 v48, 0x63, v233
	s_nop 0
	v_cndmask_b32_e32 v67, v224, v67, vcc
	v_cmp_le_i32_e32 vcc, v48, v229
	v_add_u32_e32 v48, 0x48, v233
	s_nop 0
	v_cndmask_b32_e32 v99, v224, v99, vcc
	v_cmp_le_i32_e32 vcc, v48, v229
	v_add_u32_e32 v48, 0x68, v233
	s_nop 0
	v_cndmask_b32_e32 v68, v224, v68, vcc
	v_cmp_le_i32_e32 vcc, v48, v229
	v_add_u32_e32 v48, 0x49, v233
	s_nop 0
	v_cndmask_b32_e32 v100, v224, v100, vcc
	v_cmp_le_i32_e32 vcc, v48, v229
	v_add_u32_e32 v48, 0x69, v233
	s_nop 0
	v_cndmask_b32_e32 v69, v224, v69, vcc
	v_cmp_le_i32_e32 vcc, v48, v229
	v_add_u32_e32 v48, 0x4a, v233
	s_nop 0
	v_cndmask_b32_e32 v101, v224, v101, vcc
	v_cmp_le_i32_e32 vcc, v48, v229
	v_add_u32_e32 v48, 0x6a, v233
	s_nop 0
	v_cndmask_b32_e32 v70, v224, v70, vcc
	v_cmp_le_i32_e32 vcc, v48, v229
	v_add_u32_e32 v48, 0x4b, v233
	s_nop 0
	v_cndmask_b32_e32 v102, v224, v102, vcc
	v_cmp_le_i32_e32 vcc, v48, v229
	v_add_u32_e32 v48, 0x6b, v233
	s_nop 0
	v_cndmask_b32_e32 v71, v224, v71, vcc
	v_cmp_le_i32_e32 vcc, v48, v229
	v_add_u32_e32 v48, 0x50, v233
	s_nop 0
	v_cndmask_b32_e32 v103, v224, v103, vcc
	v_cmp_le_i32_e32 vcc, v48, v229
	v_add_u32_e32 v48, 0x70, v233
	s_nop 0
	v_cndmask_b32_e32 v72, v224, v72, vcc
	v_cmp_le_i32_e32 vcc, v48, v229
	v_add_u32_e32 v48, 0x51, v233
	s_nop 0
	v_cndmask_b32_e32 v104, v224, v104, vcc
	v_cmp_le_i32_e32 vcc, v48, v229
	v_add_u32_e32 v48, 0x71, v233
	s_nop 0
	v_cndmask_b32_e32 v73, v224, v73, vcc
	v_cmp_le_i32_e32 vcc, v48, v229
	v_add_u32_e32 v48, 0x52, v233
	s_nop 0
	v_cndmask_b32_e32 v105, v224, v105, vcc
	v_cmp_le_i32_e32 vcc, v48, v229
	v_add_u32_e32 v48, 0x72, v233
	s_nop 0
	v_cndmask_b32_e32 v74, v224, v74, vcc
	v_cmp_le_i32_e32 vcc, v48, v229
	v_add_u32_e32 v48, 0x53, v233
	s_nop 0
	v_cndmask_b32_e32 v106, v224, v106, vcc
	v_cmp_le_i32_e32 vcc, v48, v229
	v_add_u32_e32 v48, 0x73, v233
	s_nop 0
	v_cndmask_b32_e32 v75, v224, v75, vcc
	v_cmp_le_i32_e32 vcc, v48, v229
	v_add_u32_e32 v48, 0x58, v233
	s_nop 0
	v_cndmask_b32_e32 v107, v224, v107, vcc
	v_cmp_le_i32_e32 vcc, v48, v229
	v_add_u32_e32 v48, 0x78, v233
	s_nop 0
	v_cndmask_b32_e32 v76, v224, v76, vcc
	v_cmp_le_i32_e32 vcc, v48, v229
	v_add_u32_e32 v48, 0x59, v233
	s_nop 0
	v_cndmask_b32_e32 v108, v224, v108, vcc
	v_cmp_le_i32_e32 vcc, v48, v229
	v_add_u32_e32 v48, 0x79, v233
	s_nop 0
	v_cndmask_b32_e32 v77, v224, v77, vcc
	v_cmp_le_i32_e32 vcc, v48, v229
	v_add_u32_e32 v48, 0x5a, v233
	s_nop 0
	v_cndmask_b32_e32 v109, v224, v109, vcc
	v_cmp_le_i32_e32 vcc, v48, v229
	v_add_u32_e32 v48, 0x7a, v233
	s_nop 0
	v_cndmask_b32_e32 v78, v224, v78, vcc
	v_cmp_le_i32_e32 vcc, v48, v229
	v_add_u32_e32 v48, 0x5b, v233
	s_nop 0
	v_cndmask_b32_e32 v110, v224, v110, vcc
	v_cmp_le_i32_e32 vcc, v48, v229
	v_add_u32_e32 v48, 0x7b, v233
	s_nop 0
	v_cndmask_b32_e32 v79, v224, v79, vcc
	v_cmp_le_i32_e32 vcc, v48, v229
	s_nop 1
	v_cndmask_b32_e32 v111, v224, v111, vcc

.LBB0_776:
.LBB0_777:
	s_add_i32 s22, s15, 1
	s_and_b32 s17, s22, 3
	s_mul_i32 s23, s17, 0x3400
	v_add_u32_e32 v80, s23, v228
	ds_read_b128 v[164:167], v80
	ds_read_b128 v[168:171], v80 offset:32
	ds_read_b128 v[172:175], v80 offset:6656
	ds_read_b128 v[176:179], v80 offset:6688
	ds_read_b128 v[180:183], v80 offset:64
	ds_read_b128 v[184:187], v80 offset:96
	ds_read_b128 v[188:191], v80 offset:6720
	ds_read_b128 v[192:195], v80 offset:6752
	ds_read_b128 v[234:237], v80 offset:128
	ds_read_b128 v[238:241], v80 offset:160
	ds_read_b128 v[242:245], v80 offset:6784
	ds_read_b128 v[160:163], v80 offset:6816
	s_waitcnt lgkmcnt(11)
	v_mfma_f32_32x32x16_bf16 v[80:95], v[164:167], v[112:115], v[32:47]
	v_exp_f32_e32 v64, v64
	v_exp_f32_e32 v66, v66
	v_exp_f32_e32 v68, v68
	v_exp_f32_e32 v164, v96
	v_exp_f32_e32 v65, v65
	v_exp_f32_e32 v165, v97
	v_exp_f32_e32 v70, v70
	v_add_f32_e32 v96, v66, v64
	v_exp_f32_e32 v67, v67
	v_add_f32_e32 v96, v68, v96
	v_add_f32_e32 v96, v70, v96
	s_waitcnt lgkmcnt(10)
	v_mfma_f32_32x32x16_bf16 v[80:95], v[168:171], v[116:119], v[80:95]
	v_exp_f32_e32 v169, v99
	v_exp_f32_e32 v168, v98
	v_add_f32_e32 v98, v67, v65
	v_exp_f32_e32 v166, v100
	v_add_f32_e32 v99, v169, v165
	v_exp_f32_e32 v69, v69
	v_exp_f32_e32 v167, v101
	v_exp_f32_e32 v170, v102
	v_add_f32_e32 v97, v168, v164
	v_add_f32_e32 v97, v166, v97
	v_add_f32_e32 v98, v69, v98
	v_add_f32_e32 v99, v167, v99
	v_add_f32_e32 v97, v170, v97
	s_waitcnt lgkmcnt(7)
	v_mfma_f32_32x32x16_bf16 v[80:95], v[180:183], v[120:123], v[80:95]
	v_exp_f32_e32 v71, v71
	v_exp_f32_e32 v171, v103
	v_exp_f32_e32 v180, v72
	v_exp_f32_e32 v181, v104
	v_exp_f32_e32 v182, v73
	v_exp_f32_e32 v183, v105
	v_add_f32_e32 v98, v71, v98
	v_add_f32_e32 v99, v171, v99
	v_add_f32_e32 v72, v180, v96
	v_add_f32_e32 v73, v181, v97
	v_add_f32_e32 v96, v182, v98
	v_add_f32_e32 v97, v183, v99
	s_waitcnt lgkmcnt(6)
	v_mfma_f32_32x32x16_bf16 v[80:95], v[184:187], v[124:127], v[80:95]
	v_exp_f32_e32 v184, v74
	v_exp_f32_e32 v185, v106
	v_exp_f32_e32 v186, v75
	v_exp_f32_e32 v187, v107
	v_add_f32_e32 v72, v184, v72
	v_add_f32_e32 v73, v185, v73
	v_add_f32_e32 v74, v186, v96
	v_add_f32_e32 v75, v187, v97
	s_waitcnt lgkmcnt(3)
	v_mfma_f32_32x32x16_bf16 v[80:95], v[234:237], v[128:131], v[80:95]
	v_exp_f32_e32 v236, v77
	v_exp_f32_e32 v234, v76
	v_exp_f32_e32 v235, v108
	v_exp_f32_e32 v237, v109
	v_exp_f32_e32 v79, v79
	v_add_f32_e32 v74, v236, v74
	v_add_f32_e32 v72, v234, v72
	v_add_f32_e32 v73, v235, v73
	v_add_f32_e32 v75, v237, v75
	v_add_f32_e32 v74, v79, v74
	v_cvt_pk_bf16_f32 v76, v180, v182
	v_cvt_pk_bf16_f32 v77, v184, v186
	s_waitcnt lgkmcnt(2)
	v_mfma_f32_32x32x16_bf16 v[80:95], v[238:241], v[132:135], v[80:95]
	v_exp_f32_e32 v238, v78
	v_exp_f32_e32 v239, v110
	v_exp_f32_e32 v240, v111
	v_add_f32_e32 v72, v238, v72
	v_add_f32_e32 v73, v239, v73
	v_add_f32_e32 v75, v240, v75
	v_add_f32_e32 v72, v73, v72
	v_add_f32_e32 v73, v75, v74
	v_cvt_pk_bf16_f32 v74, v68, v69
	v_cvt_pk_bf16_f32 v75, v70, v71
	v_mfma_f32_32x32x16_bf16 v[96:111], v[172:175], v[112:115], v[32:47]
	v_add_f32_e32 v172, v73, v72
	v_cvt_pk_bf16_f32 v72, v64, v65
	v_cvt_pk_bf16_f32 v73, v66, v67
	v_cvt_pk_bf16_f32 v64, v164, v165
	v_cvt_pk_bf16_f32 v65, v168, v169
	v_cvt_pk_bf16_f32 v66, v166, v167
	v_cvt_pk_bf16_f32 v67, v170, v171
	v_mfma_f32_32x32x16_bf16 v[96:111], v[176:179], v[116:119], v[96:111]
	v_cvt_pk_bf16_f32 v78, v234, v236
	v_cvt_pk_bf16_f32 v79, v238, v79
	v_cvt_pk_bf16_f32 v68, v181, v183
	v_cvt_pk_bf16_f32 v69, v185, v187
	v_cvt_pk_bf16_f32 v70, v235, v237
	v_cvt_pk_bf16_f32 v71, v239, v240
	v_add_f32_e32 v233, v233, v172
	v_mfma_f32_32x32x16_bf16 v[96:111], v[188:191], v[120:123], v[96:111]
	v_mfma_f32_32x32x16_bf16 v[96:111], v[192:195], v[124:127], v[96:111]
	s_waitcnt lgkmcnt(1)
	v_mfma_f32_32x32x16_bf16 v[96:111], v[242:245], v[128:131], v[96:111]
	s_and_b32 s15, s15, 2
	s_waitcnt lgkmcnt(0)
	v_mfma_f32_32x32x16_bf16 v[96:111], v[160:163], v[132:135], v[96:111]
	s_mul_i32 s23, s15, 0x3000
	v_add_u32_e32 v164, s23, v231
	ds_read_b64_tr_b16 v[192:193], v164 offset:53248
	ds_read_b64_tr_b16 v[194:195], v164 offset:54784
	ds_read_b64_tr_b16 v[190:191], v164 offset:54848
	ds_read_b64_tr_b16 v[188:189], v164 offset:53312
	ds_read_b64_tr_b16 v[184:185], v164 offset:56320
	ds_read_b64_tr_b16 v[186:187], v164 offset:57856
	ds_read_b64_tr_b16 v[182:183], v164 offset:57920
	ds_read_b64_tr_b16 v[180:181], v164 offset:56384
	ds_read_b64_tr_b16 v[176:177], v164 offset:59392
	ds_read_b64_tr_b16 v[178:179], v164 offset:60928
	ds_read_b64_tr_b16 v[174:175], v164 offset:60992
	ds_read_b64_tr_b16 v[172:173], v164 offset:59456
	ds_read_b64_tr_b16 v[168:169], v164 offset:62464
	ds_read_b64_tr_b16 v[170:171], v164 offset:64000
	ds_read_b64_tr_b16 v[166:167], v164 offset:64064
	ds_read_b64_tr_b16 v[164:165], v164 offset:62528
	s_cmp_lt_i32 s22, s2
	s_cbranch_scc1 .LBB0_779
	v_subrev_u32_e32 v160, 32, v232
	v_cmp_le_i32_e32 vcc, v232, v229
	s_nop 1
	v_cndmask_b32_e32 v96, v224, v96, vcc
	v_cmp_lt_i32_e32 vcc, v160, v229
	s_nop 1
	v_cndmask_b32_e32 v81, v224, v81, vcc
	v_cmp_le_i32_e32 vcc, v160, v229
	v_add_u32_e32 v160, 1, v232
	s_nop 0
	v_cndmask_b32_e32 v80, v224, v80, vcc
	v_cmp_le_i32_e32 vcc, v160, v229
	v_subrev_u32_e32 v160, 30, v232
	s_nop 0
	v_cndmask_b32_e32 v97, v224, v97, vcc
	v_cmp_le_i32_e32 vcc, v160, v229
	v_add_u32_e32 v160, 2, v232
	s_nop 0
	v_cndmask_b32_e32 v82, v224, v82, vcc
	v_cmp_le_i32_e32 vcc, v160, v229
	v_subrev_u32_e32 v160, 29, v232
	s_nop 0
	v_cndmask_b32_e32 v98, v224, v98, vcc
	v_cmp_le_i32_e32 vcc, v160, v229
	v_add_u32_e32 v160, 3, v232
	s_nop 0
	v_cndmask_b32_e32 v83, v224, v83, vcc
	v_cmp_le_i32_e32 vcc, v160, v229
	v_subrev_u32_e32 v160, 24, v232
	s_nop 0
	v_cndmask_b32_e32 v99, v224, v99, vcc
	v_cmp_le_i32_e32 vcc, v160, v229
	v_add_u32_e32 v160, 8, v232
	s_nop 0
	v_cndmask_b32_e32 v84, v224, v84, vcc
	v_cmp_le_i32_e32 vcc, v160, v229
	v_subrev_u32_e32 v160, 23, v232
	s_nop 0
	v_cndmask_b32_e32 v100, v224, v100, vcc
	v_cmp_le_i32_e32 vcc, v160, v229
	v_add_u32_e32 v160, 9, v232
	s_nop 0
	v_cndmask_b32_e32 v85, v224, v85, vcc
	v_cmp_le_i32_e32 vcc, v160, v229
	v_subrev_u32_e32 v160, 22, v232
	s_nop 0
	v_cndmask_b32_e32 v101, v224, v101, vcc
	v_cmp_le_i32_e32 vcc, v160, v229
	v_add_u32_e32 v160, 10, v232
	s_nop 0
	v_cndmask_b32_e32 v86, v224, v86, vcc
	v_cmp_le_i32_e32 vcc, v160, v229
	v_subrev_u32_e32 v160, 21, v232
	s_nop 0
	v_cndmask_b32_e32 v102, v224, v102, vcc
	v_cmp_le_i32_e32 vcc, v160, v229
	v_add_u32_e32 v160, 11, v232
	s_nop 0
	v_cndmask_b32_e32 v87, v224, v87, vcc
	v_cmp_le_i32_e32 vcc, v160, v229
	v_add_u32_e32 v160, -16, v232
	s_nop 0
	v_cndmask_b32_e32 v103, v224, v103, vcc
	v_cmp_le_i32_e32 vcc, v160, v229
	v_add_u32_e32 v160, 16, v232
	s_nop 0
	v_cndmask_b32_e32 v88, v224, v88, vcc
	v_cmp_le_i32_e32 vcc, v160, v229
	v_add_u32_e32 v160, -15, v232
	s_nop 0
	v_cndmask_b32_e32 v104, v224, v104, vcc
	v_cmp_le_i32_e32 vcc, v160, v229
	v_add_u32_e32 v160, 17, v232
	s_nop 0
	v_cndmask_b32_e32 v89, v224, v89, vcc
	v_cmp_le_i32_e32 vcc, v160, v229
	v_add_u32_e32 v160, -14, v232
	s_nop 0
	v_cndmask_b32_e32 v105, v224, v105, vcc
	v_cmp_le_i32_e32 vcc, v160, v229
	v_add_u32_e32 v160, 18, v232
	s_nop 0
	v_cndmask_b32_e32 v90, v224, v90, vcc
	v_cmp_le_i32_e32 vcc, v160, v229
	v_add_u32_e32 v160, -13, v232
	s_nop 0
	v_cndmask_b32_e32 v106, v224, v106, vcc
	v_cmp_le_i32_e32 vcc, v160, v229
	v_add_u32_e32 v160, 19, v232
	s_nop 0
	v_cndmask_b32_e32 v91, v224, v91, vcc
	v_cmp_le_i32_e32 vcc, v160, v229
	v_add_u32_e32 v160, -8, v232
	s_nop 0
	v_cndmask_b32_e32 v107, v224, v107, vcc
	v_cmp_le_i32_e32 vcc, v160, v229
	v_add_u32_e32 v160, 24, v232
	s_nop 0
	v_cndmask_b32_e32 v92, v224, v92, vcc
	v_cmp_le_i32_e32 vcc, v160, v229
	v_add_u32_e32 v160, -7, v232
	s_nop 0
	v_cndmask_b32_e32 v108, v224, v108, vcc
	v_cmp_le_i32_e32 vcc, v160, v229
	v_add_u32_e32 v160, 25, v232
	s_nop 0
	v_cndmask_b32_e32 v93, v224, v93, vcc
	v_cmp_le_i32_e32 vcc, v160, v229
	v_add_u32_e32 v160, -6, v232
	s_nop 0
	v_cndmask_b32_e32 v109, v224, v109, vcc
	v_cmp_le_i32_e32 vcc, v160, v229
	v_add_u32_e32 v160, 26, v232
	s_nop 0
	v_cndmask_b32_e32 v94, v224, v94, vcc
	v_cmp_le_i32_e32 vcc, v160, v229
	v_add_u32_e32 v160, -5, v232
	s_nop 0
	v_cndmask_b32_e32 v110, v224, v110, vcc
	v_cmp_le_i32_e32 vcc, v160, v229
	v_add_u32_e32 v160, 27, v232
	s_nop 0
	v_cndmask_b32_e32 v95, v224, v95, vcc
	v_cmp_le_i32_e32 vcc, v160, v229
	s_nop 1
	v_cndmask_b32_e32 v111, v224, v111, vcc

.LBB0_781:
	s_and_b32 s22, s11, 2
	s_mul_i32 s23, s22, 0x3400
	v_add_u32_e32 v64, s23, v228
	ds_read_b128 v[164:167], v64
	ds_read_b128 v[168:171], v64 offset:32
	ds_read_b128 v[172:175], v64 offset:6656
	ds_read_b128 v[176:179], v64 offset:6688
	ds_read_b128 v[180:183], v64 offset:64
	ds_read_b128 v[184:187], v64 offset:96
	ds_read_b128 v[188:191], v64 offset:6720
	ds_read_b128 v[192:195], v64 offset:6752
	ds_read_b128 v[234:237], v64 offset:128
	ds_read_b128 v[238:241], v64 offset:160
	ds_read_b128 v[242:245], v64 offset:6784
	ds_read_b128 v[160:163], v64 offset:6816
	s_waitcnt lgkmcnt(11)
	v_mfma_f32_32x32x16_bf16 v[64:79], v[164:167], v[112:115], v[32:47]
	v_exp_f32_e32 v80, v80
	v_exp_f32_e32 v96, v96
	v_exp_f32_e32 v81, v81
	v_exp_f32_e32 v97, v97
	v_exp_f32_e32 v82, v82
	v_exp_f32_e32 v98, v98
	v_exp_f32_e32 v83, v83
	v_add_f32_e32 v164, v82, v80
	v_add_f32_e32 v165, v98, v96
	v_add_f32_e32 v166, v83, v81
	s_waitcnt lgkmcnt(10)
	v_mfma_f32_32x32x16_bf16 v[64:79], v[168:171], v[116:119], v[64:79]
	v_exp_f32_e32 v99, v99
	v_exp_f32_e32 v84, v84
	v_exp_f32_e32 v100, v100
	v_exp_f32_e32 v85, v85
	v_exp_f32_e32 v101, v101
	v_exp_f32_e32 v86, v86
	v_exp_f32_e32 v102, v102
	v_add_f32_e32 v167, v99, v97
	v_add_f32_e32 v164, v84, v164
	v_add_f32_e32 v165, v100, v165
	v_exp_f32_e32 v87, v87
	v_add_f32_e32 v166, v85, v166
	v_add_f32_e32 v167, v101, v167
	v_add_f32_e32 v164, v86, v164
	v_add_f32_e32 v165, v102, v165
	s_waitcnt lgkmcnt(7)
	v_mfma_f32_32x32x16_bf16 v[64:79], v[180:183], v[120:123], v[64:79]
	v_exp_f32_e32 v168, v88
	v_exp_f32_e32 v169, v89
	v_exp_f32_e32 v103, v103
	v_add_f32_e32 v166, v87, v166
	v_exp_f32_e32 v104, v104
	v_exp_f32_e32 v105, v105
	v_add_f32_e32 v88, v168, v164
	v_add_f32_e32 v164, v169, v166
	v_exp_f32_e32 v166, v90
	v_add_f32_e32 v167, v103, v167
	v_add_f32_e32 v89, v104, v165
	v_add_f32_e32 v165, v105, v167
	v_exp_f32_e32 v167, v91
	v_exp_f32_e32 v107, v107
	v_add_f32_e32 v88, v166, v88
	s_waitcnt lgkmcnt(6)
	v_mfma_f32_32x32x16_bf16 v[64:79], v[184:187], v[124:127], v[64:79]
	v_exp_f32_e32 v106, v106
	v_add_f32_e32 v90, v167, v164
	v_add_f32_e32 v91, v107, v165
	v_exp_f32_e32 v164, v92
	v_exp_f32_e32 v108, v108
	v_exp_f32_e32 v165, v93
	v_exp_f32_e32 v109, v109
	v_add_f32_e32 v89, v106, v89
	v_add_f32_e32 v88, v164, v88
	v_add_f32_e32 v89, v108, v89
	v_add_f32_e32 v90, v165, v90
	v_add_f32_e32 v91, v109, v91
	s_waitcnt lgkmcnt(3)
	v_mfma_f32_32x32x16_bf16 v[64:79], v[234:237], v[128:131], v[64:79]
	v_exp_f32_e32 v170, v94
	v_exp_f32_e32 v110, v110
	v_exp_f32_e32 v95, v95
	v_exp_f32_e32 v111, v111
	v_add_f32_e32 v88, v170, v88
	v_add_f32_e32 v89, v110, v89
	v_add_f32_e32 v90, v95, v90
	v_add_f32_e32 v91, v111, v91
	v_add_f32_e32 v88, v89, v88
	v_add_f32_e32 v89, v91, v90
	v_add_f32_e32 v171, v88, v89
	s_waitcnt lgkmcnt(2)
	v_mfma_f32_32x32x16_bf16 v[64:79], v[238:241], v[132:135], v[64:79]
	v_cvt_pk_bf16_f32 v88, v80, v81
	v_cvt_pk_bf16_f32 v89, v82, v83
	v_cvt_pk_bf16_f32 v90, v84, v85
	v_cvt_pk_bf16_f32 v91, v86, v87
	v_cvt_pk_bf16_f32 v80, v96, v97
	v_cvt_pk_bf16_f32 v81, v98, v99
	v_cvt_pk_bf16_f32 v82, v100, v101
	v_cvt_pk_bf16_f32 v83, v102, v103
	v_cvt_pk_bf16_f32 v84, v104, v105
	v_cvt_pk_bf16_f32 v85, v106, v107
	v_cvt_pk_bf16_f32 v86, v108, v109
	v_cvt_pk_bf16_f32 v87, v110, v111
	v_mfma_f32_32x32x16_bf16 v[96:111], v[172:175], v[112:115], v[32:47]
	v_cvt_pk_bf16_f32 v92, v168, v169
	v_cvt_pk_bf16_f32 v93, v166, v167
	v_cvt_pk_bf16_f32 v94, v164, v165
	v_cvt_pk_bf16_f32 v95, v170, v95
	v_mfma_f32_32x32x16_bf16 v[96:111], v[176:179], v[116:119], v[96:111]
	v_add_f32_e32 v233, v233, v171
	v_mfma_f32_32x32x16_bf16 v[96:111], v[188:191], v[120:123], v[96:111]
	v_mfma_f32_32x32x16_bf16 v[96:111], v[192:195], v[124:127], v[96:111]
	s_waitcnt lgkmcnt(1)
	v_mfma_f32_32x32x16_bf16 v[96:111], v[242:245], v[128:131], v[96:111]
	s_mulk_i32 s17, 0x3000
	v_add_u32_e32 v253, s17, v231
	ds_read_b64_tr_b16 v[192:193], v253 offset:53248
	ds_read_b64_tr_b16 v[194:195], v253 offset:54784
	ds_read_b64_tr_b16 v[190:191], v253 offset:54848
	ds_read_b64_tr_b16 v[188:189], v253 offset:53312
	ds_read_b64_tr_b16 v[184:185], v253 offset:56320
	ds_read_b64_tr_b16 v[186:187], v253 offset:57856
	ds_read_b64_tr_b16 v[182:183], v253 offset:57920
	ds_read_b64_tr_b16 v[180:181], v253 offset:56384
	ds_read_b64_tr_b16 v[176:177], v253 offset:59392
	ds_read_b64_tr_b16 v[178:179], v253 offset:60928
	ds_read_b64_tr_b16 v[174:175], v253 offset:60992
	ds_read_b64_tr_b16 v[172:173], v253 offset:59456
	ds_read_b64_tr_b16 v[168:169], v253 offset:62464
	ds_read_b64_tr_b16 v[170:171], v253 offset:64000
	ds_read_b64_tr_b16 v[166:167], v253 offset:64064
	ds_read_b64_tr_b16 v[164:165], v253 offset:62528
	s_cmp_lt_i32 s11, s2
	s_waitcnt lgkmcnt(14)
	v_mfma_f32_32x32x16_bf16 v[96:111], v[160:163], v[132:135], v[96:111]
	s_cbranch_scc1 .LBB0_783
	v_add_u32_e32 v49, 64, v232
	v_add_u32_e32 v48, 32, v232
	v_cmp_le_i32_e32 vcc, v49, v229
	s_nop 7
	v_cndmask_b32_e32 v96, v224, v96, vcc
	v_cmp_lt_i32_e32 vcc, v48, v229
	s_nop 1
	v_cndmask_b32_e32 v65, v224, v65, vcc
	v_cmp_le_i32_e32 vcc, v48, v229
	v_add_u32_e32 v48, 0x41, v232
	s_nop 0
	v_cndmask_b32_e32 v64, v224, v64, vcc
	v_cmp_le_i32_e32 vcc, v48, v229
	v_add_u32_e32 v48, 34, v232
	s_nop 0
	v_cndmask_b32_e32 v97, v224, v97, vcc
	v_cmp_le_i32_e32 vcc, v48, v229
	v_add_u32_e32 v48, 0x42, v232
	s_nop 0
	v_cndmask_b32_e32 v66, v224, v66, vcc
	v_cmp_le_i32_e32 vcc, v48, v229
	v_add_u32_e32 v48, 35, v232
	s_nop 0
	v_cndmask_b32_e32 v98, v224, v98, vcc
	v_cmp_le_i32_e32 vcc, v48, v229
	v_add_u32_e32 v48, 0x43, v232
	s_nop 0
	v_cndmask_b32_e32 v67, v224, v67, vcc
	v_cmp_le_i32_e32 vcc, v48, v229
	v_add_u32_e32 v48, 40, v232
	s_nop 0
	v_cndmask_b32_e32 v99, v224, v99, vcc
	v_cmp_le_i32_e32 vcc, v48, v229
	v_add_u32_e32 v48, 0x48, v232
	s_nop 0
	v_cndmask_b32_e32 v68, v224, v68, vcc
	v_cmp_le_i32_e32 vcc, v48, v229
	v_add_u32_e32 v48, 41, v232
	s_nop 0
	v_cndmask_b32_e32 v100, v224, v100, vcc
	v_cmp_le_i32_e32 vcc, v48, v229
	v_add_u32_e32 v48, 0x49, v232
	s_nop 0
	v_cndmask_b32_e32 v69, v224, v69, vcc
	v_cmp_le_i32_e32 vcc, v48, v229
	v_add_u32_e32 v48, 42, v232
	s_nop 0
	v_cndmask_b32_e32 v101, v224, v101, vcc
	v_cmp_le_i32_e32 vcc, v48, v229
	v_add_u32_e32 v48, 0x4a, v232
	s_nop 0
	v_cndmask_b32_e32 v70, v224, v70, vcc
	v_cmp_le_i32_e32 vcc, v48, v229
	v_add_u32_e32 v48, 43, v232
	s_nop 0
	v_cndmask_b32_e32 v102, v224, v102, vcc
	v_cmp_le_i32_e32 vcc, v48, v229
	v_add_u32_e32 v48, 0x4b, v232
	s_nop 0
	v_cndmask_b32_e32 v71, v224, v71, vcc
	v_cmp_le_i32_e32 vcc, v48, v229
	v_add_u32_e32 v48, 48, v232
	s_nop 0
	v_cndmask_b32_e32 v103, v224, v103, vcc
	v_cmp_le_i32_e32 vcc, v48, v229
	v_add_u32_e32 v48, 0x50, v232
	s_nop 0
	v_cndmask_b32_e32 v72, v224, v72, vcc
	v_cmp_le_i32_e32 vcc, v48, v229
	v_add_u32_e32 v48, 49, v232
	s_nop 0
	v_cndmask_b32_e32 v104, v224, v104, vcc
	v_cmp_le_i32_e32 vcc, v48, v229
	v_add_u32_e32 v48, 0x51, v232
	s_nop 0
	v_cndmask_b32_e32 v73, v224, v73, vcc
	v_cmp_le_i32_e32 vcc, v48, v229
	v_add_u32_e32 v48, 50, v232
	s_nop 0
	v_cndmask_b32_e32 v105, v224, v105, vcc
	v_cmp_le_i32_e32 vcc, v48, v229
	v_add_u32_e32 v48, 0x52, v232
	s_nop 0
	v_cndmask_b32_e32 v74, v224, v74, vcc
	v_cmp_le_i32_e32 vcc, v48, v229
	v_add_u32_e32 v48, 51, v232
	s_nop 0
	v_cndmask_b32_e32 v106, v224, v106, vcc
	v_cmp_le_i32_e32 vcc, v48, v229
	v_add_u32_e32 v48, 0x53, v232
	s_nop 0
	v_cndmask_b32_e32 v75, v224, v75, vcc
	v_cmp_le_i32_e32 vcc, v48, v229
	v_add_u32_e32 v48, 56, v232
	s_nop 0
	v_cndmask_b32_e32 v107, v224, v107, vcc
	v_cmp_le_i32_e32 vcc, v48, v229
	v_add_u32_e32 v48, 0x58, v232
	s_nop 0
	v_cndmask_b32_e32 v76, v224, v76, vcc
	v_cmp_le_i32_e32 vcc, v48, v229
	v_add_u32_e32 v48, 57, v232
	s_nop 0
	v_cndmask_b32_e32 v108, v224, v108, vcc
	v_cmp_le_i32_e32 vcc, v48, v229
	v_add_u32_e32 v48, 0x59, v232
	s_nop 0
	v_cndmask_b32_e32 v77, v224, v77, vcc
	v_cmp_le_i32_e32 vcc, v48, v229
	v_add_u32_e32 v48, 58, v232
	s_nop 0
	v_cndmask_b32_e32 v109, v224, v109, vcc
	v_cmp_le_i32_e32 vcc, v48, v229
	v_add_u32_e32 v48, 0x5a, v232
	s_nop 0
	v_cndmask_b32_e32 v78, v224, v78, vcc
	v_cmp_le_i32_e32 vcc, v48, v229
	v_add_u32_e32 v48, 59, v232
	s_nop 0
	v_cndmask_b32_e32 v110, v224, v110, vcc
	v_cmp_le_i32_e32 vcc, v48, v229
	v_add_u32_e32 v48, 0x5b, v232
	s_nop 0
	v_cndmask_b32_e32 v79, v224, v79, vcc
	v_cmp_le_i32_e32 vcc, v48, v229
	s_nop 1
	v_cndmask_b32_e32 v111, v224, v111, vcc

	.amdhsa_kernel _Z8mega_fwd6Params
		.amdhsa_group_segment_fixed_size 0
		.amdhsa_private_segment_fixed_size 0
		.amdhsa_kernarg_size 536
		.amdhsa_user_sgpr_count 2
		.amdhsa_user_sgpr_dispatch_ptr 0
		.amdhsa_user_sgpr_queue_ptr 0
		.amdhsa_user_sgpr_kernarg_segment_ptr 1
		.amdhsa_user_sgpr_dispatch_id 0
		.amdhsa_user_sgpr_kernarg_preload_length 0
		.amdhsa_user_sgpr_kernarg_preload_offset 0
		.amdhsa_user_sgpr_private_segment_size 0
		.amdhsa_uses_dynamic_stack 0
		.amdhsa_enable_private_segment 0
		.amdhsa_system_sgpr_workgroup_id_x 1
		.amdhsa_system_sgpr_workgroup_id_y 0
		.amdhsa_system_sgpr_workgroup_id_z 0
		.amdhsa_system_sgpr_workgroup_info 0
		.amdhsa_system_vgpr_workitem_id 2
		.amdhsa_next_free_vgpr 256
		.amdhsa_next_free_sgpr 100
		.amdhsa_accum_offset 256
		.amdhsa_reserve_vcc 1
		.amdhsa_float_round_mode_32 0
		.amdhsa_float_round_mode_16_64 0
		.amdhsa_float_denorm_mode_32 3
		.amdhsa_float_denorm_mode_16_64 3
		.amdhsa_dx10_clamp 1
		.amdhsa_ieee_mode 1
		.amdhsa_fp16_overflow 0
		.amdhsa_tg_split 0
		.amdhsa_exception_fp_ieee_invalid_op 0
		.amdhsa_exception_fp_denorm_src 0
		.amdhsa_exception_fp_ieee_div_zero 0
		.amdhsa_exception_fp_ieee_overflow 0
		.amdhsa_exception_fp_ieee_underflow 0
		.amdhsa_exception_fp_ieee_inexact 0
		.amdhsa_exception_int_div_zero 0
	.end_amdhsa_kernel

amdhsa.kernels:
  - .agpr_count:     0
    .args:
      - .offset:         0
        .size:           280
        .value_kind:     by_value
      - .offset:         280
        .size:           4
        .value_kind:     hidden_block_count_x
      - .offset:         284
        .size:           4
        .value_kind:     hidden_block_count_y
      - .offset:         288
        .size:           4
        .value_kind:     hidden_block_count_z
      - .offset:         292
        .size:           2
        .value_kind:     hidden_group_size_x
      - .offset:         294
        .size:           2
        .value_kind:     hidden_group_size_y
      - .offset:         296
        .size:           2
        .value_kind:     hidden_group_size_z
      - .offset:         298
        .size:           2
        .value_kind:     hidden_remainder_x
      - .offset:         300
        .size:           2
        .value_kind:     hidden_remainder_y
      - .offset:         302
        .size:           2
        .value_kind:     hidden_remainder_z
      - .offset:         320
        .size:           8
        .value_kind:     hidden_global_offset_x
      - .offset:         328
        .size:           8
        .value_kind:     hidden_global_offset_y
      - .offset:         336
        .size:           8
        .value_kind:     hidden_global_offset_z
      - .offset:         344
        .size:           2
        .value_kind:     hidden_grid_dims
      - .offset:         368
        .size:           8
        .value_kind:     hidden_multigrid_sync_arg
      - .offset:         400
        .size:           4
        .value_kind:     hidden_dynamic_lds_size
    .group_segment_fixed_size: 0
    .kernarg_segment_align: 8
    .kernarg_segment_size: 536
    .language:       OpenCL C
    .language_version:
      - 2
      - 0
    .max_flat_workgroup_size: 512
    .name:           _Z8mega_fwd6Params
    .private_segment_fixed_size: 0
    .sgpr_count:     106
    .sgpr_spill_count: 264
    .symbol:         _Z8mega_fwd6Params.kd
    .uniform_work_group_size: 1
    .uses_dynamic_stack: false
    .vgpr_count:     256
    .vgpr_spill_count: 0
    .wavefront_size: 64
